# indexer header staging: pass-2 share prefetched during pass 1 (held in otherwise idle registers), staging loads issued before the address math
# baseline (speedup 1.0000x reference)
; #define GAS __attribute__((address_space(1)))
; __device__ __forceinline__ void indexer_unit(const Args& a, LAS unsigned char* lds, LAS unsigned long long* maskl, int b, int qblk, int wave, int lane) {
;     ...
;     bf16x8 af[8][2]; float wv[8][4];
; #pragma unroll
;     for (int rt = 0; rt < 8; ++rt) {
;         const GAS bf16* p = z + (rowb + t0 + 2 * rt + (fr >> 3)) * ZW + ZIQ + (fr & 7) * 64 + 8 * fq;
;         af[rt][0] = __builtin_nontemporal_load((const GAS bf16x8*)p); af[rt][1] = __builtin_nontemporal_load((const GAS bf16x8*)(p + 32));
;         const u32x2 w = *(const GAS u32x2*)(z + (rowb + t0 + 2 * rt + (fq >> 1)) * ZW + ZIW + 4 * (fq & 1));
;         wv[rt][0] = bflo(w.x); wv[rt][1] = bfhi(w.x); wv[rt][2] = bflo(w.y); wv[rt][3] = bfhi(w.y);
;     }
;     const int nkt = qblk + 1;
;     bf16x8 nb0, nb1;
;     { const int k0 = wave < nkt ? wave : 0; const GAS bf16* p = ikn + (rowb + 16 * k0 + fr) * 64 + 8 * fq; nb0 = *(const GAS bf16x8*)p; nb1 = *(const GAS bf16x8*)(p + 32); }
.LBB0_1082:
	v_readlane_b32 s2, v254, 44
	v_mov_b32_e32 v76, v252
	s_or_b32 s9, s8, s2
	s_lshl_b32 s76, s9, 4
	v_and_b32_e32 v5, 63, v76
	v_readlane_b32 s2, v254, 4
	s_cmp_gt_u32 s2, s9
	v_lshlrev_b32_e32 v84, 6, v5
	s_cbranch_scc1 .Lhs_skip
	s_cmp_lg_u32 s8, 0
	s_cbranch_scc1 .Lhs_a_n
	v_readlane_b32 s98, v254, 24
	v_readlane_b32 s99, v254, 25
	v_readlane_b32 s100, v254, 46
	v_bfe_u32 v86, v252, 3, 1
	v_lshrrev_b32_e32 v87, 5, v5
	v_and_b32_e32 v88, 7, v5
	s_add_i32 s100, s100, s76
	s_add_i32 s100, s100, s85
	v_and_b32_e32 v89, 48, v5
	v_lshl_or_b32 v88, v88, 7, v89
	v_or_b32_e32 v86, s100, v86
	v_or_b32_e32 v87, s100, v87
	s_movk_i32 s101, 0x1900
	s_movk_i32 s100, 0x1d90
	v_mul_u32_u24_e32 v86, 0x1e00, v86
	v_mul_u32_u24_e32 v87, 0x1e00, v87
	v_lshrrev_b32_e32 v89, 1, v5
	v_and_b32_e32 v89, 8, v89
	v_add3_u32 v86, v86, v88, s101
	v_add3_u32 v87, v87, v89, s100
	global_load_dwordx4 v[90:93], v86, s[98:99] nt
	global_load_dwordx4 v[94:97], v86, s[98:99] offset:64 nt
	global_load_dwordx2 v[98:99], v87, s[98:99]
	v_add_u32_e32 v86, 0x1e000, v86
	v_add_u32_e32 v87, 0x1e000, v87
	global_load_dwordx4 v[186:189], v86, s[98:99] nt
	global_load_dwordx4 v[190:193], v86, s[98:99] offset:64 nt
	global_load_dwordx2 v[194:195], v87, s[98:99]
.Lhs_a_n:
	v_readlane_b32 s14, v254, 46
	v_readlane_b32 s4, v254, 24
	s_add_i32 s2, s76, s14
	v_bfe_u32 v57, v76, 3, 1
	v_readlane_b32 s5, v254, 25
	v_and_b32_e32 v2, 0x1c0, v84
	s_nop 0
	v_mov_b64_e32 v[46:47], s[4:5]
	s_movk_i32 s10, 0x1e00
	v_lshlrev_b32_e32 v48, 1, v2
	v_mov_b32_e32 v49, v4
	v_lshrrev_b32_e32 v119, 5, v5
	v_and_b32_e32 v74, 48, v5
	v_mov_b32_e32 v75, v4
	s_mov_b64 s[12:13], 0x1900
	s_or_b32 s3, s2, 2
	s_movk_i32 s11, 0x1000
	s_or_b32 s3, s2, 4
	s_or_b32 s3, s2, 6
	s_or_b32 s3, s2, 8
	s_or_b32 s3, s2, 10
	s_or_b32 s3, s2, 12
	v_or_b32_e32 v54, s3, v57
	v_mad_u64_u32 v[54:55], s[4:5], v54, s10, v[46:47]
	v_lshl_add_u64 v[54:55], v[54:55], 0, v[48:49]
	v_lshl_add_u64 v[54:55], v[54:55], 0, v[74:75]
	v_add_co_u32_e32 v56, vcc, s11, v54
	s_mov_b64 s[6:7], vcc
	s_or_b32 s4, s2, 14
	v_and_b32_e32 v77, 15, v76
	v_readlane_b32 s2, v254, 47
	s_nop 1
	v_or_b32_e32 v66, s2, v77
	v_mov_b32_e32 v67, v4
	v_readlane_b32 s2, v254, 26
	v_lshlrev_b64 v[66:67], 7, v[66:67]
	v_readlane_b32 s3, v254, 27
	s_nop 1
	v_lshl_add_u64 v[66:67], s[2:3], 0, v[66:67]
	v_lshl_add_u64 v[70:71], v[66:67], 0, v[74:75]
	v_cmp_lt_i32_e32 vcc, v227, v226
	global_load_dwordx4 v[66:69], v[70:71], off offset:64
	global_load_dwordx4 v[70:73], v[70:71], off
	s_lshl_b32 s100, s85, 10
	s_lshl_b32 s101, s85, 8
	v_lshl_add_u32 v88, v5, 4, s100
	v_lshl_add_u32 v89, v5, 3, s101
	s_cmp_lg_u32 s8, 0
	s_cbranch_scc1 .Lhs_b_n
	s_waitcnt vmcnt(5)
	ds_write_b128 v88, v[90:93]
	ds_write_b128 v88, v[94:97] offset:1024
	ds_write_b64 v89, v[98:99] offset:16384
	s_branch .Lhs_c_n
.Lhs_b_n:
	s_waitcnt vmcnt(2)
	ds_write_b128 v88, v[186:189]
	ds_write_b128 v88, v[190:193] offset:1024
	ds_write_b64 v89, v[194:195] offset:16384
.Lhs_c_n:
	s_waitcnt lgkmcnt(0)
	s_barrier
	v_lshlrev_b32_e32 v88, 4, v5
	v_lshlrev_b32_e32 v89, 3, v5
	ds_read_b128 v[0:3], v88 offset:0
	ds_read_b128 v[6:9], v88 offset:1024
	ds_read_b128 v[14:17], v88 offset:2048
	ds_read_b128 v[10:13], v88 offset:3072
	ds_read_b128 v[18:21], v88 offset:4096
	ds_read_b128 v[22:25], v88 offset:5120
	ds_read_b128 v[30:33], v88 offset:6144
	ds_read_b128 v[26:29], v88 offset:7168
	ds_read_b128 v[34:37], v88 offset:8192
	ds_read_b128 v[38:41], v88 offset:9216
	ds_read_b128 v[42:45], v88 offset:10240
	ds_read_b128 v[50:53], v88 offset:11264
	ds_read_b128 v[54:57], v88 offset:12288
	ds_read_b128 v[58:61], v88 offset:13312
	ds_read_b128 v[46:49], v88 offset:14336
	ds_read_b128 v[62:65], v88 offset:15360
	ds_read_b64 v[78:79], v89 offset:16384
	ds_read_b64 v[80:81], v89 offset:16896
	ds_read_b64 v[82:83], v89 offset:17408
	ds_read_b64 v[100:101], v89 offset:17920
	ds_read_b64 v[104:105], v89 offset:18432
	ds_read_b64 v[108:109], v89 offset:18944
	ds_read_b64 v[112:113], v89 offset:19456
	ds_read_b64 v[116:117], v89 offset:19968
	s_waitcnt lgkmcnt(0)
	s_barrier
	s_waitcnt vmcnt(0)
	v_lshlrev_b32_e32 v93, 16, v82
	v_and_b32_e32 v94, 0xffff0000, v82
	v_lshlrev_b32_e32 v95, 16, v83
	v_and_b32_e32 v96, 0xffff0000, v83
	v_lshl_add_u64 v[82:83], s[2:3], 0, v[74:75]
	v_cndmask_b32_e32 v74, v253, v227, vcc
	v_lshlrev_b32_e32 v118, 2, v74
	v_and_b32_e32 v74, 16, v76
	v_cmp_eq_u32_e64 s[6:7], 0, v74
	v_lshlrev_b32_e32 v74, 2, v77
	v_lshl_or_b32 v74, v119, 13, v74
	v_readlane_b32 s2, v254, 36
	v_lshlrev_b32_e32 v85, 16, v78
	v_and_b32_e32 v86, 0xffff0000, v78
	v_lshlrev_b32_e32 v87, 16, v79
	v_and_b32_e32 v88, 0xffff0000, v79
	v_lshlrev_b32_e32 v89, 16, v80
	v_and_b32_e32 v90, 0xffff0000, v80
	v_lshlrev_b32_e32 v91, 16, v81
	v_and_b32_e32 v92, 0xffff0000, v81
	v_lshlrev_b32_e32 v97, 16, v100
	v_and_b32_e32 v98, 0xffff0000, v100
	v_lshlrev_b32_e32 v99, 16, v101
	v_and_b32_e32 v100, 0xffff0000, v101
	v_lshlrev_b32_e32 v101, 16, v104
	v_and_b32_e32 v102, 0xffff0000, v104
	v_lshlrev_b32_e32 v103, 16, v105
	v_and_b32_e32 v104, 0xffff0000, v105
	v_lshlrev_b32_e32 v105, 16, v108
	v_and_b32_e32 v106, 0xffff0000, v108
	v_lshlrev_b32_e32 v107, 16, v109
	v_and_b32_e32 v108, 0xffff0000, v109
	v_add_u32_e32 v119, s2, v74
	v_readlane_b32 s10, v254, 4
	v_lshlrev_b32_e32 v109, 16, v112
	v_and_b32_e32 v110, 0xffff0000, v112
	v_lshlrev_b32_e32 v111, 16, v113
	v_and_b32_e32 v112, 0xffff0000, v113
	v_lshlrev_b32_e32 v113, 16, v116
	v_and_b32_e32 v114, 0xffff0000, v116
	v_lshlrev_b32_e32 v115, 16, v117
	v_and_b32_e32 v116, 0xffff0000, v117
	v_or_b32_e32 v117, s14, v77
	s_branch .LBB0_1085

; #define GAS __attribute__((address_space(1)))
; __device__ __forceinline__ void indexer_unit(const Args& a, LAS unsigned char* lds, LAS unsigned long long* maskl, int b, int qblk, int wave, int lane) {
;     ...
;     bf16x8 af[8][2]; float wv[8][4];
; #pragma unroll
;     for (int rt = 0; rt < 8; ++rt) {
;         const GAS bf16* p = z + (rowb + t0 + 2 * rt + (fr >> 3)) * ZW + ZIQ + (fr & 7) * 64 + 8 * fq;
;         af[rt][0] = __builtin_nontemporal_load((const GAS bf16x8*)p); af[rt][1] = __builtin_nontemporal_load((const GAS bf16x8*)(p + 32));
;         const u32x2 w = *(const GAS u32x2*)(z + (rowb + t0 + 2 * rt + (fq >> 1)) * ZW + ZIW + 4 * (fq & 1));
;         wv[rt][0] = bflo(w.x); wv[rt][1] = bfhi(w.x); wv[rt][2] = bflo(w.y); wv[rt][3] = bfhi(w.y);
;     }
.Lhs_skip:
	s_cmp_lg_u32 s8, 0
	s_cbranch_scc1 .Lhs_a_s
	v_readlane_b32 s98, v254, 24
	v_readlane_b32 s99, v254, 25
	v_readlane_b32 s100, v254, 46
	v_bfe_u32 v86, v252, 3, 1
	v_lshrrev_b32_e32 v87, 5, v5
	v_and_b32_e32 v88, 7, v5
	s_add_i32 s100, s100, s76
	s_add_i32 s100, s100, s85
	v_and_b32_e32 v89, 48, v5
	v_lshl_or_b32 v88, v88, 7, v89
	v_or_b32_e32 v86, s100, v86
	v_or_b32_e32 v87, s100, v87
	s_movk_i32 s101, 0x1900
	s_movk_i32 s100, 0x1d90
	v_mul_u32_u24_e32 v86, 0x1e00, v86
	v_mul_u32_u24_e32 v87, 0x1e00, v87
	v_lshrrev_b32_e32 v89, 1, v5
	v_and_b32_e32 v89, 8, v89
	v_add3_u32 v86, v86, v88, s101
	v_add3_u32 v87, v87, v89, s100
	global_load_dwordx4 v[90:93], v86, s[98:99] nt
	global_load_dwordx4 v[94:97], v86, s[98:99] offset:64 nt
	global_load_dwordx2 v[98:99], v87, s[98:99]
	v_add_u32_e32 v86, 0x1e000, v86
	v_add_u32_e32 v87, 0x1e000, v87
	global_load_dwordx4 v[186:189], v86, s[98:99] nt
	global_load_dwordx4 v[190:193], v86, s[98:99] offset:64 nt
	global_load_dwordx2 v[194:195], v87, s[98:99]
.Lhs_a_s:
	s_lshl_b32 s100, s85, 10
	s_lshl_b32 s101, s85, 8
	v_lshl_add_u32 v88, v5, 4, s100
	v_lshl_add_u32 v89, v5, 3, s101
	s_cmp_lg_u32 s8, 0
	s_cbranch_scc1 .Lhs_b_s
	s_waitcnt vmcnt(3)
	ds_write_b128 v88, v[90:93]
	ds_write_b128 v88, v[94:97] offset:1024
	ds_write_b64 v89, v[98:99] offset:16384
	s_branch .Lhs_c_s
.Lhs_b_s:
	s_waitcnt vmcnt(0)
	ds_write_b128 v88, v[186:189]
	ds_write_b128 v88, v[190:193] offset:1024
	ds_write_b64 v89, v[194:195] offset:16384
.Lhs_c_s:
	s_waitcnt lgkmcnt(0)
	s_barrier
	s_barrier
